# scan: value-half unit pairs share an XCD; b_last loaded/converted only by the 16 publishing threads; o-tile stores issued after the state-update MFMAs
# speedup vs baseline: 1.0423x; 1.0093x over previous
.LBB0_1141:
	s_or_b64 exec, exec, s[4:5]
	s_cmpk_gt_u32 s50, 0xbf
	s_cselect_b64 s[46:47], -1, 0
	s_and_b64 s[4:5], s[46:47], exec
	s_cselect_b32 s3, 0x80, s50
	s_cmp_ge_i32 s2, s3
	s_cselect_b64 s[4:5], -1, 0
	s_cmpk_gt_i32 s2, 0x7f
	s_cselect_b64 s[6:7], -1, 0
	s_or_b64 s[4:5], s[4:5], s[6:7]
	s_and_b64 vcc, exec, s[4:5]
	s_barrier
	s_cbranch_vccnz .LBB0_1174
	s_movk_i32 s33, 0x4200
	s_movk_i32 s51, 0x70
	s_mov_b32 s49, 0
	v_mov_b32_e32 v1, 0
	s_movk_i32 s84, 0xf0
	v_mov_b32_e32 v137, 0x16000
	s_and_b32 s85, s2, 0x71
	s_bfe_u32 s4, s2, 0x10003
	s_lshl_b32 s4, s4, 1
	s_or_b32 s85, s85, s4
	s_bfe_u32 s4, s2, 0x20001
	s_lshl_b32 s4, s4, 2
	s_or_b32 s85, s85, s4
	s_branch .LBB0_1144

.LBB0_1150:
	s_waitcnt vmcnt(4)
	v_cvt_f32_f16_e32 v2, v156
	v_cvt_f32_f16_sdwa v3, v156 dst_sel:DWORD dst_unused:UNUSED_PAD src0_sel:WORD_1
	v_and_b32_e32 v5, 0xffff0000, v138
	v_exp_f32_e32 v114, v2
	v_exp_f32_e64 v116, -v2
	v_exp_f32_e32 v115, v3
	v_exp_f32_e64 v117, -v3
	v_lshlrev_b32_e32 v4, 16, v138
	v_lshlrev_b32_e32 v14, 16, v8
	v_and_b32_e32 v15, 0xffff0000, v8
	v_pk_mul_f32 v[114:115], v[114:115], v[14:15]
	v_pk_mul_f32 v[116:117], v[116:117], v[4:5]
	v_cvt_f32_f16_e32 v4, v157
	v_exp_f32_e32 v14, v4
	v_exp_f32_e64 v118, -v4
	v_cvt_f32_f16_sdwa v5, v157 dst_sel:DWORD dst_unused:UNUSED_PAD src0_sel:WORD_1
	v_lshlrev_b32_e32 v12, 16, v139
	v_exp_f32_e32 v15, v5
	v_exp_f32_e64 v119, -v5
	v_and_b32_e32 v13, 0xffff0000, v139
	v_lshlrev_b32_e32 v112, 16, v9
	v_and_b32_e32 v113, 0xffff0000, v9
	v_pk_mul_f32 v[120:121], v[14:15], v[112:113]
	v_pk_mul_f32 v[118:119], v[118:119], v[12:13]
	v_cvt_f32_f16_e32 v12, v158
	v_cvt_f32_f16_sdwa v13, v158 dst_sel:DWORD dst_unused:UNUSED_PAD src0_sel:WORD_1
	v_lshlrev_b32_e32 v14, 16, v140
	v_exp_f32_e32 v126, v12
	v_exp_f32_e64 v228, -v12
	v_exp_f32_e32 v127, v13
	v_exp_f32_e64 v229, -v13
	v_and_b32_e32 v15, 0xffff0000, v140
	v_lshlrev_b32_e32 v122, 16, v10
	v_and_b32_e32 v123, 0xffff0000, v10
	v_pk_mul_f32 v[122:123], v[126:127], v[122:123]
	v_pk_mul_f32 v[126:127], v[228:229], v[14:15]
	v_cvt_f32_f16_e32 v14, v159
	v_cvt_f32_f16_sdwa v15, v159 dst_sel:DWORD dst_unused:UNUSED_PAD src0_sel:WORD_1
	v_exp_f32_e32 v228, v14
	v_exp_f32_e64 v230, -v14
	v_exp_f32_e32 v229, v15
	v_exp_f32_e64 v231, -v15
	v_lshlrev_b32_e32 v112, 16, v141
	v_and_b32_e32 v113, 0xffff0000, v141
	v_lshlrev_b32_e32 v124, 16, v11
	v_and_b32_e32 v125, 0xffff0000, v11
	v_pk_mul_f32 v[124:125], v[228:229], v[124:125]
	v_pk_mul_f32 v[228:229], v[230:231], v[112:113]
	v_cvt_pk_bf16_f32 v112, v114, v115
	v_cvt_pk_bf16_f32 v115, v124, v125
	s_waitcnt vmcnt(2)
	v_cvt_f32_f16_e32 v15, v164
	v_cvt_f32_f16_sdwa v124, v164 dst_sel:DWORD dst_unused:UNUSED_PAD src0_sel:WORD_1
	v_cvt_pk_bf16_f32 v114, v122, v123
	v_cvt_pk_bf16_f32 v113, v120, v121
	v_exp_f32_e32 v120, v15
	v_exp_f32_e32 v121, v124
	v_cvt_pk_bf16_f32 v116, v116, v117
	v_cvt_pk_bf16_f32 v117, v118, v119
	v_exp_f32_e64 v122, -v15
	v_cvt_pk_bf16_f32 v118, v126, v127
	v_cvt_pk_bf16_f32 v119, v228, v229
	ds_write_b64 v173, v[112:113] offset:0
	ds_write_b64 v174, v[114:115] offset:0
	ds_write_b64 v173, v[116:117] offset:16384
	ds_write_b64 v174, v[118:119] offset:16384
	v_lshlrev_b32_e32 v116, 16, v232
	v_and_b32_e32 v117, 0xffff0000, v232
	v_pk_mul_f32 v[116:117], v[120:121], v[116:117]
	v_exp_f32_e64 v123, -v124
	v_lshlrev_b32_e32 v112, 16, v160
	v_and_b32_e32 v113, 0xffff0000, v160
	v_pk_mul_f32 v[120:121], v[122:123], v[112:113]
	v_cvt_f32_f16_e32 v123, v165
	v_cvt_f32_f16_sdwa v15, v165 dst_sel:DWORD dst_unused:UNUSED_PAD src0_sel:WORD_1
	v_exp_f32_e32 v112, v123
	v_exp_f32_e64 v122, -v123
	v_exp_f32_e32 v113, v15
	v_exp_f32_e64 v123, -v15
	v_lshlrev_b32_e32 v114, 16, v161
	v_and_b32_e32 v115, 0xffff0000, v161
	v_lshlrev_b32_e32 v118, 16, v233
	v_and_b32_e32 v119, 0xffff0000, v233
	v_pk_mul_f32 v[118:119], v[112:113], v[118:119]
	s_waitcnt vmcnt(2)
	v_cvt_f32_f16_e32 v15, v166
	v_cvt_f32_f16_sdwa v175, v166 dst_sel:DWORD dst_unused:UNUSED_PAD src0_sel:WORD_1
	v_lshlrev_b32_e32 v112, 16, v162
	v_exp_f32_e32 v228, v15
	v_exp_f32_e64 v230, -v15
	v_exp_f32_e32 v229, v175
	v_exp_f32_e64 v231, -v175
	v_and_b32_e32 v113, 0xffff0000, v162
	v_cvt_f32_f16_e32 v175, v167
	v_lshlrev_b32_e32 v124, 16, v234
	v_and_b32_e32 v125, 0xffff0000, v234
	v_pk_mul_f32 v[124:125], v[228:229], v[124:125]
	v_pk_mul_f32 v[228:229], v[230:231], v[112:113]
	v_cvt_f32_f16_sdwa v15, v167 dst_sel:DWORD dst_unused:UNUSED_PAD src0_sel:WORD_1
	v_exp_f32_e32 v112, v175
	v_exp_f32_e64 v230, -v175
	v_exp_f32_e32 v113, v15
	v_exp_f32_e64 v231, -v15
	v_pk_mul_f32 v[122:123], v[122:123], v[114:115]
	v_lshlrev_b32_e32 v114, 16, v163
	v_lshlrev_b32_e32 v126, 16, v235
	v_and_b32_e32 v127, 0xffff0000, v235
	v_and_b32_e32 v115, 0xffff0000, v163
	v_pk_mul_f32 v[126:127], v[112:113], v[126:127]
	v_pk_mul_f32 v[230:231], v[230:231], v[114:115]
	v_cvt_pk_bf16_f32 v112, v116, v117
	v_cvt_pk_bf16_f32 v113, v118, v119
	v_cvt_pk_bf16_f32 v114, v124, v125
	v_cvt_pk_bf16_f32 v115, v126, v127
	v_cvt_pk_bf16_f32 v116, v120, v121
	v_cvt_pk_bf16_f32 v117, v122, v123
	v_cvt_pk_bf16_f32 v118, v228, v229
	v_cvt_pk_bf16_f32 v119, v230, v231
	ds_write_b64 v173, v[112:113] offset:8192
	ds_write_b64 v174, v[114:115] offset:8192
	ds_write_b64 v173, v[116:117] offset:24576
	ds_write_b64 v174, v[118:119] offset:24576
	s_waitcnt vmcnt(1)
	ds_write_b128 v211, v[128:131] offset:49152
	s_waitcnt vmcnt(0)
	ds_write_b128 v211, v[132:135] offset:57344
	s_and_saveexec_b64 s[44:45], s[6:7]
	s_cbranch_execz .LBB0_1152
	v_cvt_f32_f16_e32 v112, v142
	v_cvt_f32_f16_sdwa v113, v142 dst_sel:DWORD dst_unused:UNUSED_PAD src0_sel:WORD_1
	v_cvt_f32_f16_e32 v114, v143
	v_cvt_f32_f16_sdwa v115, v143 dst_sel:DWORD dst_unused:UNUSED_PAD src0_sel:WORD_1
	v_cvt_f32_f16_e32 v2, v144
	v_cvt_f32_f16_sdwa v3, v144 dst_sel:DWORD dst_unused:UNUSED_PAD src0_sel:WORD_1
	v_cvt_f32_f16_e32 v4, v145
	v_cvt_f32_f16_sdwa v5, v145 dst_sel:DWORD dst_unused:UNUSED_PAD src0_sel:WORD_1
	v_exp_f32_e32 v112, v112
	v_exp_f32_e32 v113, v113
	v_exp_f32_e32 v114, v114
	v_exp_f32_e32 v115, v115
	v_exp_f32_e32 v2, v2
	v_exp_f32_e32 v3, v3
	v_exp_f32_e32 v4, v4
	v_exp_f32_e32 v5, v5
	v_add_u32_e32 v12, s32, v176
	ds_write_b128 v12, v[112:115]
	ds_write_b128 v12, v[2:5] offset:16

.Lscan_noq:
	v_lshl_add_u64 v[4:5], v[2:3], 1, s[76:77]
	global_load_dwordx4 v[138:141], v[4:5], off
	v_lshl_add_u64 v[4:5], v[2:3], 1, s[70:71]
	global_load_dwordx4 v[156:159], v[4:5], off
	s_add_i32 s60, s91, s86
	s_ashr_i32 s61, s60, 31
	s_lshl_b64 s[60:61], s[60:61], 10
	v_lshl_add_u64 v[4:5], v[146:147], 0, s[60:61]
	s_and_saveexec_b64 s[44:45], s[6:7]
	s_cbranch_execz .Lscan_nobl
	global_load_dwordx4 v[142:145], v[4:5], off
.Lscan_nobl:
	s_mov_b64 exec, s[44:45]
	v_lshl_add_u64 v[4:5], v[12:13], 1, s[76:77]
	global_load_dwordx4 v[160:163], v[4:5], off
	v_lshl_add_u64 v[4:5], v[12:13], 1, s[70:71]
	global_load_dwordx4 v[164:167], v[4:5], off
	s_lshl_b64 s[44:45], s[48:49], 1
	v_lshl_add_u64 v[2:3], v[152:153], 0, s[44:45]
	v_lshl_add_u64 v[4:5], v[154:155], 0, s[44:45]
	global_load_dwordx4 v[128:131], v[2:3], off
	global_load_dwordx4 v[132:135], v[4:5], off
	s_cmp_lg_u64 s[8:9], 0
	s_cbranch_scc1 .LBB0_1162
	s_and_b64 vcc, exec, s[82:83]
	s_cbranch_vccnz .Lscan_b2
	s_branch .Lscan_loads_ret

.Lscan_b2:
	s_waitcnt lgkmcnt(0)
	s_barrier
	s_and_saveexec_b64 s[44:45], s[8:9]
	s_cbranch_execz .LBB0_1171
	v_add_u32_e32 v0, v180, v192
	ds_read_b128 v[2:5], v0 offset:49152
	v_add_u32_e32 v0, v182, v192
	ds_read_b128 v[12:15], v0
	ds_read_b128 v[112:115], v0 offset:4096
	v_add_u32_e32 v0, v180, v193
	ds_read_b128 v[116:119], v0 offset:49152
	v_add_u32_e32 v0, v182, v193
	ds_read_b128 v[120:123], v0
	ds_read_b128 v[124:127], v0 offset:4096
	s_ashr_i32 s81, s80, 31
	s_lshl_b64 s[60:61], s[80:81], 11
	s_waitcnt lgkmcnt(4)
	v_mfma_f32_32x32x16_bf16 v[80:95], v[2:5], v[12:15], v[80:95]
	s_waitcnt lgkmcnt(3)
	v_mfma_f32_32x32x16_bf16 v[96:111], v[2:5], v[112:115], v[96:111]
	v_add_u32_e32 v0, v180, v195
	ds_read_b128 v[2:5], v0 offset:49152
	v_add_u32_e32 v0, v182, v195
	ds_read_b128 v[12:15], v0
	ds_read_b128 v[112:115], v0 offset:4096
	s_waitcnt lgkmcnt(4)
	v_mfma_f32_32x32x16_bf16 v[80:95], v[116:119], v[120:123], v[80:95]
	s_waitcnt lgkmcnt(3)
	v_mfma_f32_32x32x16_bf16 v[96:111], v[116:119], v[124:127], v[96:111]
	v_add_u32_e32 v0, v180, v196
	ds_read_b128 v[116:119], v0 offset:49152
	v_add_u32_e32 v0, v182, v196
	ds_read_b128 v[120:123], v0
	ds_read_b128 v[124:127], v0 offset:4096
	s_waitcnt lgkmcnt(4)
	v_mfma_f32_32x32x16_bf16 v[80:95], v[2:5], v[12:15], v[80:95]
	s_waitcnt lgkmcnt(3)
	v_mfma_f32_32x32x16_bf16 v[96:111], v[2:5], v[112:115], v[96:111]
	s_waitcnt lgkmcnt(1)
	v_mfma_f32_32x32x16_bf16 v[80:95], v[116:119], v[120:123], v[80:95]
	s_waitcnt lgkmcnt(0)
	v_mfma_f32_32x32x16_bf16 v[96:111], v[116:119], v[124:127], v[96:111]
	v_mbcnt_lo_u32_b32 v0, -1, 0
	v_mbcnt_hi_u32_b32 v0, -1, v0
	v_and_b32_e32 v120, 31, v0
	v_lshrrev_b32_e32 v121, 5, v0
	v_mul_u32_u24_e32 v120, 0x7fe, v120
	v_mul_u32_u24_e32 v121, 0x1ff0, v121
	v_sub_u32_e32 v120, v120, v121
	v_ashrrev_i32_e32 v121, 31, v120
	v_lshl_add_u64 v[124:125], v[168:169], 0, v[120:121]
	v_lshl_add_u64 v[124:125], v[124:125], 0, s[60:61]
	s_mov_b64 s[60:61], 0x10000
	v_lshl_add_u64 v[126:127], v[124:125], 0, s[60:61]
	s_nop 3
	v_cvt_pk_bf16_f32 v2, v80, v81
	v_cvt_pk_bf16_f32 v3, v82, v83
	v_cvt_pk_bf16_f32 v4, v84, v85
	v_cvt_pk_bf16_f32 v5, v86, v87
	s_nop 1
	v_permlane32_swap_b32_e32 v2, v4
	v_permlane32_swap_b32_e32 v3, v5
	v_cvt_pk_bf16_f32 v12, v88, v89
	v_cvt_pk_bf16_f32 v13, v90, v91
	v_cvt_pk_bf16_f32 v14, v92, v93
	v_cvt_pk_bf16_f32 v15, v94, v95
	s_nop 1
	v_permlane32_swap_b32_e32 v12, v14
	v_permlane32_swap_b32_e32 v13, v15
	v_cvt_pk_bf16_f32 v112, v96, v97
	v_cvt_pk_bf16_f32 v113, v98, v99
	v_cvt_pk_bf16_f32 v114, v100, v101
	v_cvt_pk_bf16_f32 v115, v102, v103
	s_nop 1
	v_permlane32_swap_b32_e32 v112, v114
	v_permlane32_swap_b32_e32 v113, v115
	v_cvt_pk_bf16_f32 v116, v104, v105
	v_cvt_pk_bf16_f32 v117, v106, v107
	v_cvt_pk_bf16_f32 v118, v108, v109
	v_cvt_pk_bf16_f32 v119, v110, v111
	s_nop 1
	v_permlane32_swap_b32_e32 v116, v118
	v_permlane32_swap_b32_e32 v117, v119

.Lscan_loads_ret:
.Lscan_tail_w03:
	s_and_saveexec_b64 s[44:45], s[8:9]
	s_cbranch_execz .LBB0_1145
	v_add_u32_e32 v0, v180, v192
	ds_read_b128 v[120:123], v0 offset:49152
	ds_read_b64_tr_b16 v[80:81], v197 offset:0
	ds_read_b64_tr_b16 v[82:83], v201 offset:1024
	ds_read_b64_tr_b16 v[84:85], v198 offset:0
	ds_read_b64_tr_b16 v[86:87], v202 offset:1024
	ds_read_b64_tr_b16 v[88:89], v199 offset:0
	ds_read_b64_tr_b16 v[90:91], v203 offset:1024
	ds_read_b64_tr_b16 v[92:93], v200 offset:0
	ds_read_b64_tr_b16 v[94:95], v204 offset:1024
	v_add_u32_e32 v0, v180, v193
	ds_read_b128 v[96:99], v0 offset:49152
	s_waitcnt lgkmcnt(7)
	v_mfma_f32_32x32x16_bf16 v[64:79], v[80:83], v[120:123], v[64:79]
	ds_read_b64_tr_b16 v[80:81], v197 offset:4096
	ds_read_b64_tr_b16 v[82:83], v201 offset:5120
	s_waitcnt lgkmcnt(7)
	v_mfma_f32_32x32x16_bf16 v[48:63], v[84:87], v[120:123], v[48:63]
	ds_read_b64_tr_b16 v[84:85], v198 offset:4096
	ds_read_b64_tr_b16 v[86:87], v202 offset:5120
	s_waitcnt lgkmcnt(7)
	v_mfma_f32_32x32x16_bf16 v[32:47], v[88:91], v[120:123], v[32:47]
	ds_read_b64_tr_b16 v[88:89], v199 offset:4096
	ds_read_b64_tr_b16 v[90:91], v203 offset:5120
	s_waitcnt lgkmcnt(7)
	v_mfma_f32_32x32x16_bf16 v[16:31], v[92:95], v[120:123], v[16:31]
	ds_read_b64_tr_b16 v[92:93], v200 offset:4096
	ds_read_b64_tr_b16 v[94:95], v204 offset:5120
	v_add_u32_e32 v0, v180, v195
	ds_read_b128 v[120:123], v0 offset:49152
	s_waitcnt lgkmcnt(7)
	v_mfma_f32_32x32x16_bf16 v[64:79], v[80:83], v[96:99], v[64:79]
	ds_read_b64_tr_b16 v[80:81], v197 offset:8192
	ds_read_b64_tr_b16 v[82:83], v201 offset:9216
	s_waitcnt lgkmcnt(7)
	v_mfma_f32_32x32x16_bf16 v[48:63], v[84:87], v[96:99], v[48:63]
	ds_read_b64_tr_b16 v[84:85], v198 offset:8192
	ds_read_b64_tr_b16 v[86:87], v202 offset:9216
	s_waitcnt lgkmcnt(7)
	v_mfma_f32_32x32x16_bf16 v[32:47], v[88:91], v[96:99], v[32:47]
	ds_read_b64_tr_b16 v[88:89], v199 offset:8192
	ds_read_b64_tr_b16 v[90:91], v203 offset:9216
	s_waitcnt lgkmcnt(7)
	v_mfma_f32_32x32x16_bf16 v[16:31], v[92:95], v[96:99], v[16:31]
	ds_read_b64_tr_b16 v[92:93], v200 offset:8192
	ds_read_b64_tr_b16 v[94:95], v204 offset:9216
	v_add_u32_e32 v0, v180, v196
	ds_read_b128 v[96:99], v0 offset:49152
	s_waitcnt lgkmcnt(7)
	v_mfma_f32_32x32x16_bf16 v[64:79], v[80:83], v[120:123], v[64:79]
	ds_read_b64_tr_b16 v[80:81], v197 offset:12288
	ds_read_b64_tr_b16 v[82:83], v201 offset:13312
	s_waitcnt lgkmcnt(7)
	v_mfma_f32_32x32x16_bf16 v[48:63], v[84:87], v[120:123], v[48:63]
	ds_read_b64_tr_b16 v[84:85], v198 offset:12288
	ds_read_b64_tr_b16 v[86:87], v202 offset:13312
	s_waitcnt lgkmcnt(7)
	v_mfma_f32_32x32x16_bf16 v[32:47], v[88:91], v[120:123], v[32:47]
	ds_read_b64_tr_b16 v[88:89], v199 offset:12288
	ds_read_b64_tr_b16 v[90:91], v203 offset:13312
	s_waitcnt lgkmcnt(7)
	v_mfma_f32_32x32x16_bf16 v[16:31], v[92:95], v[120:123], v[16:31]
	ds_read_b64_tr_b16 v[92:93], v200 offset:12288
	ds_read_b64_tr_b16 v[94:95], v204 offset:13312
	s_waitcnt lgkmcnt(6)
	v_mfma_f32_32x32x16_bf16 v[64:79], v[80:83], v[96:99], v[64:79]
	s_waitcnt lgkmcnt(4)
	v_mfma_f32_32x32x16_bf16 v[48:63], v[84:87], v[96:99], v[48:63]
	s_waitcnt lgkmcnt(2)
	v_mfma_f32_32x32x16_bf16 v[32:47], v[88:91], v[96:99], v[32:47]
	s_waitcnt lgkmcnt(0)
	v_mfma_f32_32x32x16_bf16 v[16:31], v[92:95], v[96:99], v[16:31]
	s_and_b64 vcc, exec, s[82:83]
	s_cbranch_vccz .LBB0_1145
	global_store_dwordx4 v[124:125], v[2:5], off
	global_store_dwordx4 v[124:125], v[12:15], off offset:32
	global_store_dwordx4 v[126:127], v[112:115], off
	global_store_dwordx4 v[126:127], v[116:119], off offset:32
	s_branch .LBB0_1145
